# grid barrier: XCD leader posts XGEN before its own buffer_inv (11 sites)
# baseline (speedup 1.0000x reference)
.LBB0_275:
	s_or_b64 exec, exec, s[6:7]
	s_mov_b64 s[6:7], exec
	v_mbcnt_lo_u32_b32 v0, s6, 0
	v_mbcnt_hi_u32_b32 v0, s7, v0
	v_cmp_eq_u32_e32 vcc, 0, v0
	s_waitcnt vmcnt(0)
	s_and_saveexec_b64 s[8:9], vcc
	s_cbranch_execz .LBB0_277
	s_bcnt1_i32_b64 s6, s[6:7]
	v_mov_b32_e32 v0, 0x2000
	v_mov_b32_e32 v1, s6
	global_atomic_add v0, v1, s[4:5] offset:1024
.LBB0_277:
	s_or_b64 exec, exec, s[8:9]
	buffer_inv sc1
	s_waitcnt vmcnt(0)

.LBB0_416:
	s_or_b64 exec, exec, s[6:7]
	s_mov_b64 s[6:7], exec
	v_mbcnt_lo_u32_b32 v0, s6, 0
	v_mbcnt_hi_u32_b32 v0, s7, v0
	v_cmp_eq_u32_e32 vcc, 0, v0
	s_waitcnt vmcnt(0)
	s_and_saveexec_b64 s[8:9], vcc
	s_cbranch_execz .LBB0_418
	s_bcnt1_i32_b64 s6, s[6:7]
	v_mov_b32_e32 v0, 0x2000
	v_mov_b32_e32 v1, s6
	global_atomic_add v0, v1, s[2:3] offset:1024

.LBB0_845:
	s_or_b64 exec, exec, s[4:5]
	s_mov_b64 s[4:5], exec
	v_mbcnt_lo_u32_b32 v0, s4, 0
	v_mbcnt_hi_u32_b32 v0, s5, v0
	v_cmp_eq_u32_e32 vcc, 0, v0
	s_waitcnt vmcnt(0)
	s_and_saveexec_b64 s[6:7], vcc
	s_cbranch_execz .LBB0_847
	s_bcnt1_i32_b64 s4, s[4:5]
	v_mov_b32_e32 v0, 0x2000
	v_mov_b32_e32 v1, s4
	global_atomic_add v0, v1, s[2:3] offset:1024
.LBB0_847:
	s_or_b64 exec, exec, s[6:7]
	buffer_inv sc1
	s_waitcnt vmcnt(0)

.LBB0_985:
	s_or_b64 exec, exec, s[8:9]
	s_mov_b64 s[8:9], exec
	v_mbcnt_lo_u32_b32 v0, s8, 0
	v_mbcnt_hi_u32_b32 v0, s9, v0
	v_cmp_eq_u32_e32 vcc, 0, v0
	s_waitcnt vmcnt(0)
	s_and_saveexec_b64 s[10:11], vcc
	s_cbranch_execz .LBB0_987
	s_bcnt1_i32_b64 s8, s[8:9]
	v_mov_b32_e32 v0, 0x2000
	v_mov_b32_e32 v1, s8
	global_atomic_add v0, v1, s[4:5] offset:1024
.LBB0_987:
	s_or_b64 exec, exec, s[10:11]
	buffer_inv sc1
	s_waitcnt vmcnt(0)
